# P11 seam fix-up: second grid-stride item's loads issued together with the first (two-item software pipelining, straight-line)
# baseline (speedup 1.0000x reference)
.LBB0_981:
	s_or_b64 exec, exec, s[0:1]
	s_waitcnt lgkmcnt(0)
	s_barrier
	v_mbcnt_lo_u32_b32 v0, -1, 0
	v_mbcnt_hi_u32_b32 v0, -1, v0
	s_mov_b32 s0, 0x2c000
	v_add_u32_e32 v36, s35, v0
	v_cmp_gt_i32_e32 vcc, s0, v36
	s_and_saveexec_b64 s[0:1], vcc
	s_cbranch_execz .LBB0_994
	s_lshl_b32 s35, s84, 9
	v_lshlrev_b32_e32 v37, 3, v36
	s_lshl_b32 s50, s84, 12
	s_mov_b64 s[18:19], 0
	s_mov_b32 s51, 0x2e8ba2e9
	s_movk_i32 s52, 0x158
	s_movk_i32 s53, 0x1600
	v_mov_b32_e32 v33, 0
	s_mov_b64 s[22:23], 0x5600
	s_mov_b64 s[24:25], 0xac00
	s_mov_b64 s[36:37], 0x2b00
	s_movk_i32 s54, 0x2000
	s_mov_b64 s[38:39], 0x8100
	s_mov_b32 s55, 0x8000
	s_mov_b64 s[40:41], 0xd700
	s_mov_b32 s56, 0xd000
	s_movk_i32 s57, 0x80
	s_mov_b32 s58, 0x2bfff
	v_mov_b32_e32 v38, 0x6e00
	v_mov_b32_e32 v39, 0x5800
	v_mov_b32_e32 v40, 0x1600
	v_mul_hi_i32 v0, v36, s51
	v_lshrrev_b32_e32 v1, 31, v0
	v_ashrrev_i32_e32 v0, 6, v0
	v_add_u32_e32 v41, v0, v1
	v_mul_i32_i24_e32 v0, 0x160, v41
	v_sub_u32_e32 v1, v36, v0
	v_lshlrev_b32_e32 v0, 3, v0
	v_sub_u32_e32 v34, v37, v0
	v_and_b32_e32 v43, 3, v41
	v_ashrrev_i32_e32 v42, 2, v41
	v_ashrrev_i32_e32 v35, 31, v34
	v_cmp_gt_i32_e32 vcc, s52, v1
	v_mov_b32_e32 v3, 0
	v_mov_b32_e32 v2, 0
	v_mov_b32_e32 v1, 0
	v_mov_b32_e32 v0, 0
	s_and_saveexec_b64 s[42:43], vcc
	s_cbranch_execz .Lp11a_skip
	v_cmp_eq_u32_e64 s[6:7], 2, v43
	v_cmp_eq_u32_e64 s[8:9], 1, v43
	v_cmp_eq_u32_e64 s[10:11], 0, v43
	v_cndmask_b32_e64 v0, v38, v39, s[6:7]
	v_cndmask_b32_e64 v2, v0, v40, s[8:9]
	v_cndmask_b32_e64 v0, 4, 3, s[6:7]
	v_cndmask_b32_e64 v0, v0, 0, s[8:9]
	v_cndmask_b32_e64 v8, v0, -1, s[10:11]
	v_mul_hi_i32_i24_e32 v1, 0x16000, v42
	v_mul_i32_i24_e32 v0, 0x16000, v42
	v_lshl_add_u64 v[0:1], s[14:15], 0, v[0:1]
	v_lshl_add_u64 v[24:25], v[34:35], 1, v[0:1]
	v_cndmask_b32_e64 v0, v2, 0, s[10:11]
	v_lshlrev_b32_e32 v32, 1, v0
	v_lshl_add_u64 v[0:1], v[24:25], 0, v[32:33]
	v_add_co_u32_e32 v4, vcc, 0x1000, v0
	v_and_b32_e32 v9, 31, v41
	s_nop 0
	v_addc_co_u32_e32 v5, vcc, 0, v1, vcc
	global_load_dwordx4 v[0:3], v[0:1], off
	s_nop 0
	global_load_dwordx4 v[4:7], v[4:5], off offset:1536
	v_mul_i32_i24_e32 v16, 0x1600, v8
	v_mov_b32_e32 v12, 0
	v_cmp_ne_u32_e32 vcc, 0, v9
	v_ashrrev_i32_e32 v17, 31, v16
	v_mov_b32_e32 v8, 0
	v_mov_b32_e32 v9, 0
	v_mov_b32_e32 v10, 0
	v_mov_b32_e32 v11, 0
	s_and_saveexec_b64 s[44:45], vcc
	s_cbranch_execz .Lp11a_988
	v_lshl_add_u64 v[8:9], v[16:17], 1, v[24:25]
	global_load_dwordx4 v[8:11], v[8:9], off

.Lp11a_992:
	s_or_b64 exec, exec, s[8:9]
	v_mov_b32_e32 v17, 0
	v_mov_b32_e32 v18, 0
	v_mov_b32_e32 v19, 0
	s_and_saveexec_b64 s[8:9], s[6:7]
	s_cbranch_execz .Lp11a_w
	v_lshl_add_u64 v[16:17], v[26:27], 1, v[24:25]
	v_add_co_u32_e32 v16, vcc, 0x1000, v16
	s_nop 1
	v_addc_co_u32_e32 v17, vcc, 0, v17, vcc
	global_load_dwordx4 v[16:19], v[16:17], off offset:1536
.Lp11a_w:
	s_or_b64 exec, exec, s[8:9]
	v_lshlrev_b64 v[24:25], 2, v[34:35]
	v_lshl_add_u64 v[76:77], s[46:47], 0, v[24:25]
	v_add_co_u32_e32 v26, vcc, 0x5000, v76
	v_lshl_add_u64 v[78:79], s[48:49], 0, v[24:25]
	s_nop 0
	v_addc_co_u32_e32 v27, vcc, 0, v77, vcc
	v_add_co_u32_e32 v24, vcc, s54, v76
	global_load_dwordx4 v[48:51], v[26:27], off offset:1536
	s_nop 0
	v_addc_co_u32_e32 v25, vcc, 0, v77, vcc
	global_load_dwordx4 v[56:59], v[24:25], off offset:2816
	v_add_co_u32_e32 v24, vcc, s55, v76
	global_load_dwordx4 v[44:47], v[76:77], off
	s_nop 0
	v_addc_co_u32_e32 v25, vcc, 0, v77, vcc
	global_load_dwordx4 v[60:63], v[24:25], off offset:256
	v_add_co_u32_e32 v24, vcc, s56, v76
	global_load_dwordx4 v[52:55], v[78:79], off
	s_nop 0
	v_addc_co_u32_e32 v25, vcc, 0, v77, vcc
	global_load_dwordx4 v[64:67], v[24:25], off offset:1792
	v_add_co_u32_e32 v24, vcc, s54, v78
	v_lshl_add_u64 v[88:89], v[76:77], 0, s[22:23]
	s_nop 0
	v_addc_co_u32_e32 v25, vcc, 0, v79, vcc
	global_load_dwordx4 v[68:71], v[24:25], off offset:2816
	v_add_co_u32_e32 v24, vcc, 0xa000, v76
	v_lshl_add_u64 v[96:97], v[76:77], 0, s[24:25]
	s_nop 0
	v_addc_co_u32_e32 v25, vcc, 0, v77, vcc
	global_load_dwordx4 v[72:75], v[24:25], off offset:3072
	global_load_dwordx4 v[28:31], v[76:77], off offset:16
	s_nop 0
	global_load_dwordx4 v[24:27], v[78:79], off offset:16
	v_lshl_add_u64 v[80:81], v[76:77], 0, s[36:37]
	v_lshl_add_u64 v[82:83], v[76:77], 0, s[38:39]
	v_lshl_add_u64 v[84:85], v[76:77], 0, s[40:41]
	v_lshl_add_u64 v[92:93], v[78:79], 0, s[36:37]
	global_load_dwordx4 v[76:79], v[80:81], off offset:16
	s_nop 0
	global_load_dwordx4 v[80:83], v[82:83], off offset:16
	s_nop 0
	global_load_dwordx4 v[84:87], v[84:85], off offset:16
	s_nop 0
	global_load_dwordx4 v[88:91], v[88:89], off offset:16
	s_nop 0
	global_load_dwordx4 v[92:95], v[92:93], off offset:16
	s_nop 0
	global_load_dwordx4 v[96:99], v[96:97], off offset:16
.Lp11a_skip:
	s_mov_b64 s[60:61], exec
	s_or_b64 exec, exec, s[42:43]
	v_add_u32_e32 v160, s35, v36
	v_add_u32_e32 v161, s50, v37
	v_mov_b32_e32 v157, 0
	v_mov_b32_e32 v162, v38
	v_mov_b32_e32 v163, v39
	v_mov_b32_e32 v164, v40
	s_mov_b64 s[64:65], 0
	s_mov_b64 s[66:67], 0
	v_cmp_ge_i32_e32 vcc, s58, v160
	s_and_saveexec_b64 s[62:63], vcc
	s_cbranch_execz .Lp11b_ld_done
	v_mul_hi_i32 v124, v160, s51
	v_lshrrev_b32_e32 v125, 31, v124
	v_ashrrev_i32_e32 v124, 6, v124
	v_add_u32_e32 v165, v124, v125
	v_mul_i32_i24_e32 v124, 0x160, v165
	v_sub_u32_e32 v125, v160, v124
	v_lshlrev_b32_e32 v124, 3, v124
	v_sub_u32_e32 v158, v161, v124
	v_and_b32_e32 v167, 3, v165
	v_ashrrev_i32_e32 v166, 2, v165
	v_ashrrev_i32_e32 v159, 31, v158
	v_cmp_gt_i32_e32 vcc, s52, v125
	v_mov_b32_e32 v127, 0
	v_mov_b32_e32 v126, 0
	v_mov_b32_e32 v125, 0
	v_mov_b32_e32 v124, 0
	s_and_saveexec_b64 s[66:67], vcc
	s_cbranch_execz .Lp11b_skip
	v_cmp_eq_u32_e64 s[6:7], 2, v167
	v_cmp_eq_u32_e64 s[8:9], 1, v167
	v_cmp_eq_u32_e64 s[10:11], 0, v167
	v_cndmask_b32_e64 v124, v162, v163, s[6:7]
	v_cndmask_b32_e64 v126, v124, v164, s[8:9]
	v_cndmask_b32_e64 v124, 4, 3, s[6:7]
	v_cndmask_b32_e64 v124, v124, 0, s[8:9]
	v_cndmask_b32_e64 v132, v124, -1, s[10:11]
	v_mul_hi_i32_i24_e32 v125, 0x16000, v166
	v_mul_i32_i24_e32 v124, 0x16000, v166
	v_lshl_add_u64 v[124:125], s[14:15], 0, v[124:125]
	v_lshl_add_u64 v[148:149], v[158:159], 1, v[124:125]
	v_cndmask_b32_e64 v124, v126, 0, s[10:11]
	v_lshlrev_b32_e32 v156, 1, v124
	v_lshl_add_u64 v[124:125], v[148:149], 0, v[156:157]
	v_add_co_u32_e32 v128, vcc, 0x1000, v124
	v_and_b32_e32 v133, 31, v165
	s_nop 0
	v_addc_co_u32_e32 v129, vcc, 0, v125, vcc
	global_load_dwordx4 v[124:127], v[124:125], off
	s_nop 0
	global_load_dwordx4 v[128:131], v[128:129], off offset:1536
	v_mul_i32_i24_e32 v140, 0x1600, v132
	v_mov_b32_e32 v136, 0
	v_cmp_ne_u32_e32 vcc, 0, v133
	v_ashrrev_i32_e32 v141, 31, v140
	v_mov_b32_e32 v132, 0
	v_mov_b32_e32 v133, 0
	v_mov_b32_e32 v134, 0
	v_mov_b32_e32 v135, 0
	s_and_saveexec_b64 s[44:45], vcc
	s_cbranch_execz .Lp11b_988
	v_lshl_add_u64 v[132:133], v[140:141], 1, v[148:149]
	global_load_dwordx4 v[132:135], v[132:133], off
.Lp11b_988:
	s_or_b64 exec, exec, s[44:45]
	v_mov_b32_e32 v137, 0
	v_mov_b32_e32 v138, 0
	v_mov_b32_e32 v139, 0
	s_and_saveexec_b64 s[44:45], vcc
	s_cbranch_execz .Lp11b_990
	v_lshl_add_u64 v[136:137], v[140:141], 1, v[148:149]
	v_add_co_u32_e32 v136, vcc, 0x1000, v136
	s_nop 1
	v_addc_co_u32_e32 v137, vcc, 0, v137, vcc
	global_load_dwordx4 v[136:139], v[136:137], off offset:1536
.Lp11b_990:
	s_or_b64 exec, exec, s[44:45]
	v_and_b32_e32 v141, 28, v165
	v_cmp_ne_u32_e32 vcc, 0, v141
	v_cndmask_b32_e64 v141, 3, 2, s[6:7]
	v_cndmask_b32_e64 v141, v141, -1, s[8:9]
	v_cndmask_b32_e64 v141, v141, -2, s[10:11]
	v_cmp_lt_u32_e64 s[6:7], 1, v167
	v_mul_i32_i24_e32 v150, 0x1600, v141
	v_mov_b32_e32 v140, 0
	s_or_b64 s[6:7], vcc, s[6:7]
	v_ashrrev_i32_e32 v151, 31, v150
	v_mov_b32_e32 v144, 0
	v_mov_b32_e32 v145, 0
	v_mov_b32_e32 v146, 0
	v_mov_b32_e32 v147, 0
	s_and_saveexec_b64 s[8:9], s[6:7]
	s_cbranch_execz .Lp11b_992
	v_lshl_add_u64 v[142:143], v[150:151], 1, v[148:149]
	global_load_dwordx4 v[144:147], v[142:143], off
.Lp11b_992:
	s_or_b64 exec, exec, s[8:9]
	v_mov_b32_e32 v141, 0
	v_mov_b32_e32 v142, 0
	v_mov_b32_e32 v143, 0
	s_and_saveexec_b64 s[8:9], s[6:7]
	s_cbranch_execz .Lp11b_w
	v_lshl_add_u64 v[140:141], v[150:151], 1, v[148:149]
	v_add_co_u32_e32 v140, vcc, 0x1000, v140
	s_nop 1
	v_addc_co_u32_e32 v141, vcc, 0, v141, vcc
	global_load_dwordx4 v[140:143], v[140:141], off offset:1536
.Lp11b_w:
	s_or_b64 exec, exec, s[8:9]
	v_lshlrev_b64 v[148:149], 2, v[158:159]
	v_lshl_add_u64 v[200:201], s[46:47], 0, v[148:149]
	v_add_co_u32_e32 v150, vcc, 0x5000, v200
	v_lshl_add_u64 v[202:203], s[48:49], 0, v[148:149]
	s_nop 0
	v_addc_co_u32_e32 v151, vcc, 0, v201, vcc
	v_add_co_u32_e32 v148, vcc, s54, v200
	global_load_dwordx4 v[172:175], v[150:151], off offset:1536
	s_nop 0
	v_addc_co_u32_e32 v149, vcc, 0, v201, vcc
	global_load_dwordx4 v[180:183], v[148:149], off offset:2816
	v_add_co_u32_e32 v148, vcc, s55, v200
	global_load_dwordx4 v[168:171], v[200:201], off
	s_nop 0
	v_addc_co_u32_e32 v149, vcc, 0, v201, vcc
	global_load_dwordx4 v[184:187], v[148:149], off offset:256
	v_add_co_u32_e32 v148, vcc, s56, v200
	global_load_dwordx4 v[176:179], v[202:203], off
	s_nop 0
	v_addc_co_u32_e32 v149, vcc, 0, v201, vcc
	global_load_dwordx4 v[188:191], v[148:149], off offset:1792
	v_add_co_u32_e32 v148, vcc, s54, v202
	v_lshl_add_u64 v[212:213], v[200:201], 0, s[22:23]
	s_nop 0
	v_addc_co_u32_e32 v149, vcc, 0, v203, vcc
	global_load_dwordx4 v[192:195], v[148:149], off offset:2816
	v_add_co_u32_e32 v148, vcc, 0xa000, v200
	v_lshl_add_u64 v[220:221], v[200:201], 0, s[24:25]
	s_nop 0
	v_addc_co_u32_e32 v149, vcc, 0, v201, vcc
	global_load_dwordx4 v[196:199], v[148:149], off offset:3072
	global_load_dwordx4 v[152:155], v[200:201], off offset:16
	s_nop 0
	global_load_dwordx4 v[148:151], v[202:203], off offset:16
	v_lshl_add_u64 v[204:205], v[200:201], 0, s[36:37]
	v_lshl_add_u64 v[206:207], v[200:201], 0, s[38:39]
	v_lshl_add_u64 v[208:209], v[200:201], 0, s[40:41]
	v_lshl_add_u64 v[216:217], v[202:203], 0, s[36:37]
	global_load_dwordx4 v[200:203], v[204:205], off offset:16
	s_nop 0
	global_load_dwordx4 v[204:207], v[206:207], off offset:16
	s_nop 0
	global_load_dwordx4 v[208:211], v[208:209], off offset:16
	s_nop 0
	global_load_dwordx4 v[212:215], v[212:213], off offset:16
	s_nop 0
	global_load_dwordx4 v[216:219], v[216:217], off offset:16
	s_nop 0
	global_load_dwordx4 v[220:223], v[220:221], off offset:16
.Lp11b_skip:
	s_mov_b64 s[64:65], exec
.Lp11b_ld_done:
	s_mov_b64 exec, s[60:61]
	s_waitcnt vmcnt(0)
	v_lshlrev_b32_e32 v103, 16, v12
	v_lshlrev_b32_e32 v102, 16, v8
	v_lshlrev_b32_e32 v105, 16, v16
	v_lshlrev_b32_e32 v104, 16, v20
	v_lshlrev_b32_e32 v101, 16, v4
	v_lshlrev_b32_e32 v100, 16, v0
	v_and_b32_e32 v106, 0xffff0000, v0
	v_and_b32_e32 v109, 0xffff0000, v12
	v_and_b32_e32 v108, 0xffff0000, v8
	v_and_b32_e32 v111, 0xffff0000, v16
	v_and_b32_e32 v110, 0xffff0000, v20
	v_and_b32_e32 v107, 0xffff0000, v4
	v_lshlrev_b32_e32 v114, 16, v9
	v_lshlrev_b32_e32 v115, 16, v13
	v_lshlrev_b32_e32 v113, 16, v5
	v_lshlrev_b32_e32 v112, 16, v1
	v_and_b32_e32 v8, 0xffff0000, v21
	v_and_b32_e32 v5, 0xffff0000, v5
	v_mov_b32_e32 v120, v48
	v_mov_b32_e32 v117, v56
	v_mov_b32_e32 v116, v44
	v_mov_b32_e32 v56, v45
	v_mov_b32_e32 v121, v60
	v_pk_mul_f32 v[44:45], v[120:121], v[102:103]
	v_mov_b32_e32 v60, v49
	v_pk_fma_f32 v[44:45], v[116:117], v[104:105], v[44:45]
	v_mov_b32_e32 v118, v52
	v_pk_mul_f32 v[48:49], v[60:61], v[108:109]
	v_mov_b32_e32 v123, v64
	v_pk_fma_f32 v[48:49], v[56:57], v[110:111], v[48:49]
	v_lshlrev_b32_e32 v52, 16, v21
	v_mov_b32_e32 v56, v46
	v_mov_b32_e32 v57, v58
	v_mov_b32_e32 v58, v47
	v_mov_b32_e32 v119, v68
	v_mov_b32_e32 v68, v53
	v_lshlrev_b32_e32 v53, 16, v17
	v_mov_b32_e32 v122, v72
	v_pk_fma_f32 v[44:45], v[122:123], v[100:101], v[44:45]
	v_mov_b32_e32 v64, v73
	v_pk_add_f32 v[44:45], v[118:119], v[44:45]
	v_pk_fma_f32 v[48:49], v[64:65], v[106:107], v[48:49]
	v_mul_f32_e32 v0, 0xbfb8aa3b, v44
	v_exp_f32_e32 v0, v0
	v_pk_add_f32 v[48:49], v[68:69], v[48:49]
	v_mov_b32_e32 v20, v88
	v_mul_f32_e32 v4, 0xbfb8aa3b, v48
	v_add_f32_e32 v0, 1.0, v0
	v_rcp_f32_e32 v0, v0
	v_exp_f32_e32 v4, v4
	v_mov_b32_e32 v21, v80
	v_mov_b32_e32 v80, v89
	v_mul_f32_e32 v0, v44, v0
	v_mul_f32_e32 v32, v0, v45
	v_mov_b32_e32 v44, v50
	v_mov_b32_e32 v45, v62
	v_add_f32_e32 v4, 1.0, v4
	v_pk_mul_f32 v[44:45], v[44:45], v[114:115]
	v_rcp_f32_e32 v4, v4
	v_pk_fma_f32 v[44:45], v[56:57], v[52:53], v[44:45]
	v_mov_b32_e32 v52, v74
	v_mov_b32_e32 v53, v66
	v_pk_fma_f32 v[44:45], v[52:53], v[112:113], v[44:45]
	v_mov_b32_e32 v52, v54
	v_mov_b32_e32 v53, v70
	v_pk_add_f32 v[44:45], v[52:53], v[44:45]
	v_mul_f32_e32 v12, v48, v4
	v_mul_f32_e32 v0, 0xbfb8aa3b, v44
	v_exp_f32_e32 v16, v0
	v_and_b32_e32 v4, 0xffff0000, v1
	v_and_b32_e32 v1, 0xffff0000, v13
	v_and_b32_e32 v0, 0xffff0000, v9
	v_mov_b32_e32 v62, v51
	v_and_b32_e32 v9, 0xffff0000, v17
	v_pk_mul_f32 v[0:1], v[62:63], v[0:1]
	v_mov_b32_e32 v66, v75
	v_pk_fma_f32 v[0:1], v[58:59], v[8:9], v[0:1]
	v_mov_b32_e32 v70, v55
	v_pk_fma_f32 v[0:1], v[66:67], v[4:5], v[0:1]
	v_lshlrev_b32_e32 v9, 16, v14
	v_pk_add_f32 v[0:1], v[70:71], v[0:1]
	v_lshlrev_b32_e32 v8, 16, v10
	v_mul_f32_e32 v4, 0xbfb8aa3b, v0
	v_exp_f32_e32 v4, v4
	v_mul_f32_e32 v46, v12, v49
	v_add_f32_e32 v5, 1.0, v16
	v_lshlrev_b32_e32 v13, 16, v18
	v_add_f32_e32 v4, 1.0, v4
	v_lshlrev_b32_e32 v12, 16, v22
	v_mov_b32_e32 v16, v28
	v_mov_b32_e32 v17, v76
	v_pk_mul_f32 v[8:9], v[20:21], v[8:9]
	v_rcp_f32_e32 v47, v5
	v_rcp_f32_e32 v48, v4
	v_lshlrev_b32_e32 v5, 16, v6
	v_lshlrev_b32_e32 v4, 16, v2
	v_pk_fma_f32 v[8:9], v[16:17], v[12:13], v[8:9]
	v_mov_b32_e32 v12, v96
	v_mov_b32_e32 v13, v84
	v_pk_fma_f32 v[4:5], v[12:13], v[4:5], v[8:9]
	v_mov_b32_e32 v8, v24
	v_mov_b32_e32 v9, v92
	v_pk_add_f32 v[4:5], v[8:9], v[4:5]
	v_and_b32_e32 v13, 0xffff0000, v14
	v_mul_f32_e32 v8, 0xbfb8aa3b, v4
	v_exp_f32_e32 v8, v8
	v_and_b32_e32 v12, 0xffff0000, v10
	v_mul_f32_e32 v9, v44, v47
	v_and_b32_e32 v17, 0xffff0000, v18
	v_add_f32_e32 v8, 1.0, v8
	v_and_b32_e32 v16, 0xffff0000, v22
	v_mov_b32_e32 v76, v29
	v_pk_mul_f32 v[12:13], v[80:81], v[12:13]
	v_mul_f32_e32 v24, v9, v45
	v_rcp_f32_e32 v20, v8
	v_and_b32_e32 v9, 0xffff0000, v6
	v_and_b32_e32 v8, 0xffff0000, v2
	v_pk_fma_f32 v[12:13], v[76:77], v[16:17], v[12:13]
	v_mov_b32_e32 v84, v97
	v_pk_fma_f32 v[8:9], v[84:85], v[8:9], v[12:13]
	v_mov_b32_e32 v92, v25
	v_pk_add_f32 v[8:9], v[92:93], v[8:9]
	v_mul_f32_e32 v0, v0, v48
	v_mul_f32_e32 v2, 0xbfb8aa3b, v8
	v_exp_f32_e32 v2, v2
	v_mul_f32_e32 v10, v0, v1
	v_mul_f32_e32 v0, v4, v20
	v_mul_f32_e32 v14, v0, v5
	v_lshlrev_b32_e32 v4, 16, v11
	v_lshlrev_b32_e32 v5, 16, v15
	v_mov_b32_e32 v20, v90
	v_mov_b32_e32 v21, v82
	v_add_f32_e32 v0, 1.0, v2
	v_lshlrev_b32_e32 v12, 16, v23
	v_lshlrev_b32_e32 v13, 16, v19
	v_mov_b32_e32 v16, v30
	v_mov_b32_e32 v17, v78
	v_pk_mul_f32 v[4:5], v[20:21], v[4:5]
	v_rcp_f32_e32 v18, v0
	v_lshlrev_b32_e32 v1, 16, v7
	v_lshlrev_b32_e32 v0, 16, v3
	v_pk_fma_f32 v[4:5], v[16:17], v[12:13], v[4:5]
	v_mov_b32_e32 v12, v98
	v_mov_b32_e32 v13, v86
	v_pk_fma_f32 v[0:1], v[12:13], v[0:1], v[4:5]
	v_mov_b32_e32 v4, v26
	v_mov_b32_e32 v5, v94
	v_pk_add_f32 v[0:1], v[4:5], v[0:1]
	v_and_b32_e32 v4, 0xffff0000, v3
	v_mul_f32_e32 v2, 0xbfb8aa3b, v0
	v_exp_f32_e32 v12, v2
	v_and_b32_e32 v3, 0xffff0000, v15
	v_and_b32_e32 v2, 0xffff0000, v11
	v_mov_b32_e32 v82, v91
	v_and_b32_e32 v5, 0xffff0000, v7
	v_and_b32_e32 v7, 0xffff0000, v19
	v_and_b32_e32 v6, 0xffff0000, v23
	v_mov_b32_e32 v78, v31
	v_pk_mul_f32 v[2:3], v[82:83], v[2:3]
	v_mov_b32_e32 v86, v99
	v_pk_fma_f32 v[2:3], v[78:79], v[6:7], v[2:3]
	v_mov_b32_e32 v94, v27
	v_pk_fma_f32 v[2:3], v[86:87], v[4:5], v[2:3]
	v_add_f32_e32 v6, 1.0, v12
	v_pk_add_f32 v[2:3], v[94:95], v[2:3]
	v_rcp_f32_e32 v6, v6
	v_mul_f32_e32 v4, 0xbfb8aa3b, v2
	v_exp_f32_e32 v4, v4
	v_mul_f32_e32 v5, v8, v18
	v_mul_f32_e32 v0, v0, v6
	v_mul_f32_e32 v6, v0, v1
	v_add_f32_e32 v4, 1.0, v4
	v_rcp_f32_e32 v4, v4
	v_mul_f32_e32 v5, v5, v9
	v_mul_f32_e32 v0, v2, v4
	v_mul_f32_e32 v3, v0, v3
	v_cvt_pk_bf16_f32 v0, v32, v46
	v_cvt_pk_bf16_f32 v1, v24, v10
	v_cvt_pk_bf16_f32 v2, v14, v5
	v_cvt_pk_bf16_f32 v3, v6, v3
	s_or_b64 exec, exec, s[42:43]
	v_and_b32_e32 v4, 1, v41
	v_lshlrev_b32_e32 v5, 6, v43
	v_and_or_b32 v4, v5, s57, v4
	v_lshl_or_b32 v7, v42, 8, v4
	v_mov_b64_e32 v[4:5], s[16:17]
	v_ashrrev_i32_e32 v6, 31, v42
	v_mad_u64_u32 v[4:5], s[6:7], v7, s53, v[4:5]
	v_mad_i32_i24 v5, v6, s53, v5
	v_lshl_add_u64 v[4:5], v[34:35], 1, v[4:5]
	global_store_dwordx4 v[4:5], v[0:3], off
	s_mov_b64 exec, s[64:65]
	v_lshlrev_b32_e32 v227, 16, v136
	v_lshlrev_b32_e32 v226, 16, v132
	v_lshlrev_b32_e32 v229, 16, v140
	v_lshlrev_b32_e32 v228, 16, v144
	v_lshlrev_b32_e32 v225, 16, v128
	v_lshlrev_b32_e32 v224, 16, v124
	v_and_b32_e32 v230, 0xffff0000, v124
	v_and_b32_e32 v233, 0xffff0000, v136
	v_and_b32_e32 v232, 0xffff0000, v132
	v_and_b32_e32 v235, 0xffff0000, v140
	v_and_b32_e32 v234, 0xffff0000, v144
	v_and_b32_e32 v231, 0xffff0000, v128
	v_lshlrev_b32_e32 v238, 16, v133
	v_lshlrev_b32_e32 v239, 16, v137
	v_lshlrev_b32_e32 v237, 16, v129
	v_lshlrev_b32_e32 v236, 16, v125
	v_and_b32_e32 v132, 0xffff0000, v145
	v_and_b32_e32 v129, 0xffff0000, v129
	v_mov_b32_e32 v244, v172
	v_mov_b32_e32 v241, v180
	v_mov_b32_e32 v240, v168
	v_mov_b32_e32 v180, v169
	v_mov_b32_e32 v245, v184
	v_pk_mul_f32 v[168:169], v[244:245], v[226:227]
	v_mov_b32_e32 v184, v173
	v_pk_fma_f32 v[168:169], v[240:241], v[228:229], v[168:169]
	v_mov_b32_e32 v242, v176
	v_pk_mul_f32 v[172:173], v[184:185], v[232:233]
	v_mov_b32_e32 v247, v188
	v_pk_fma_f32 v[172:173], v[180:181], v[234:235], v[172:173]
	v_lshlrev_b32_e32 v176, 16, v145
	v_mov_b32_e32 v180, v170
	v_mov_b32_e32 v181, v182
	v_mov_b32_e32 v182, v171
	v_mov_b32_e32 v243, v192
	v_mov_b32_e32 v192, v177
	v_lshlrev_b32_e32 v177, 16, v141
	v_mov_b32_e32 v246, v196
	v_pk_fma_f32 v[168:169], v[246:247], v[224:225], v[168:169]
	v_mov_b32_e32 v188, v197
	v_pk_add_f32 v[168:169], v[242:243], v[168:169]
	v_pk_fma_f32 v[172:173], v[188:189], v[230:231], v[172:173]
	v_mul_f32_e32 v124, 0xbfb8aa3b, v168
	v_exp_f32_e32 v124, v124
	v_pk_add_f32 v[172:173], v[192:193], v[172:173]
	v_mov_b32_e32 v144, v212
	v_mul_f32_e32 v128, 0xbfb8aa3b, v172
	v_add_f32_e32 v124, 1.0, v124
	v_rcp_f32_e32 v124, v124
	v_exp_f32_e32 v128, v128
	v_mov_b32_e32 v145, v204
	v_mov_b32_e32 v204, v213
	v_mul_f32_e32 v124, v168, v124
	v_mul_f32_e32 v156, v124, v169
	v_mov_b32_e32 v168, v174
	v_mov_b32_e32 v169, v186
	v_add_f32_e32 v128, 1.0, v128
	v_pk_mul_f32 v[168:169], v[168:169], v[238:239]
	v_rcp_f32_e32 v128, v128
	v_pk_fma_f32 v[168:169], v[180:181], v[176:177], v[168:169]
	v_mov_b32_e32 v176, v198
	v_mov_b32_e32 v177, v190
	v_pk_fma_f32 v[168:169], v[176:177], v[236:237], v[168:169]
	v_mov_b32_e32 v176, v178
	v_mov_b32_e32 v177, v194
	v_pk_add_f32 v[168:169], v[176:177], v[168:169]
	v_mul_f32_e32 v136, v172, v128
	v_mul_f32_e32 v124, 0xbfb8aa3b, v168
	v_exp_f32_e32 v140, v124
	v_and_b32_e32 v128, 0xffff0000, v125
	v_and_b32_e32 v125, 0xffff0000, v137
	v_and_b32_e32 v124, 0xffff0000, v133
	v_mov_b32_e32 v186, v175
	v_and_b32_e32 v133, 0xffff0000, v141
	v_pk_mul_f32 v[124:125], v[186:187], v[124:125]
	v_mov_b32_e32 v190, v199
	v_pk_fma_f32 v[124:125], v[182:183], v[132:133], v[124:125]
	v_mov_b32_e32 v194, v179
	v_pk_fma_f32 v[124:125], v[190:191], v[128:129], v[124:125]
	v_lshlrev_b32_e32 v133, 16, v138
	v_pk_add_f32 v[124:125], v[194:195], v[124:125]
	v_lshlrev_b32_e32 v132, 16, v134
	v_mul_f32_e32 v128, 0xbfb8aa3b, v124
	v_exp_f32_e32 v128, v128
	v_mul_f32_e32 v170, v136, v173
	v_add_f32_e32 v129, 1.0, v140
	v_lshlrev_b32_e32 v137, 16, v142
	v_add_f32_e32 v128, 1.0, v128
	v_lshlrev_b32_e32 v136, 16, v146
	v_mov_b32_e32 v140, v152
	v_mov_b32_e32 v141, v200
	v_pk_mul_f32 v[132:133], v[144:145], v[132:133]
	v_rcp_f32_e32 v171, v129
	v_rcp_f32_e32 v172, v128
	v_lshlrev_b32_e32 v129, 16, v130
	v_lshlrev_b32_e32 v128, 16, v126
	v_pk_fma_f32 v[132:133], v[140:141], v[136:137], v[132:133]
	v_mov_b32_e32 v136, v220
	v_mov_b32_e32 v137, v208
	v_pk_fma_f32 v[128:129], v[136:137], v[128:129], v[132:133]
	v_mov_b32_e32 v132, v148
	v_mov_b32_e32 v133, v216
	v_pk_add_f32 v[128:129], v[132:133], v[128:129]
	v_and_b32_e32 v137, 0xffff0000, v138
	v_mul_f32_e32 v132, 0xbfb8aa3b, v128
	v_exp_f32_e32 v132, v132
	v_and_b32_e32 v136, 0xffff0000, v134
	v_mul_f32_e32 v133, v168, v171
	v_and_b32_e32 v141, 0xffff0000, v142
	v_add_f32_e32 v132, 1.0, v132
	v_and_b32_e32 v140, 0xffff0000, v146
	v_mov_b32_e32 v200, v153
	v_pk_mul_f32 v[136:137], v[204:205], v[136:137]
	v_mul_f32_e32 v148, v133, v169
	v_rcp_f32_e32 v144, v132
	v_and_b32_e32 v133, 0xffff0000, v130
	v_and_b32_e32 v132, 0xffff0000, v126
	v_pk_fma_f32 v[136:137], v[200:201], v[140:141], v[136:137]
	v_mov_b32_e32 v208, v221
	v_pk_fma_f32 v[132:133], v[208:209], v[132:133], v[136:137]
	v_mov_b32_e32 v216, v149
	v_pk_add_f32 v[132:133], v[216:217], v[132:133]
	v_mul_f32_e32 v124, v124, v172
	v_mul_f32_e32 v126, 0xbfb8aa3b, v132
	v_exp_f32_e32 v126, v126
	v_mul_f32_e32 v134, v124, v125
	v_mul_f32_e32 v124, v128, v144
	v_mul_f32_e32 v138, v124, v129
	v_lshlrev_b32_e32 v128, 16, v135
	v_lshlrev_b32_e32 v129, 16, v139
	v_mov_b32_e32 v144, v214
	v_mov_b32_e32 v145, v206
	v_add_f32_e32 v124, 1.0, v126
	v_lshlrev_b32_e32 v136, 16, v147
	v_lshlrev_b32_e32 v137, 16, v143
	v_mov_b32_e32 v140, v154
	v_mov_b32_e32 v141, v202
	v_pk_mul_f32 v[128:129], v[144:145], v[128:129]
	v_rcp_f32_e32 v142, v124
	v_lshlrev_b32_e32 v125, 16, v131
	v_lshlrev_b32_e32 v124, 16, v127
	v_pk_fma_f32 v[128:129], v[140:141], v[136:137], v[128:129]
	v_mov_b32_e32 v136, v222
	v_mov_b32_e32 v137, v210
	v_pk_fma_f32 v[124:125], v[136:137], v[124:125], v[128:129]
	v_mov_b32_e32 v128, v150
	v_mov_b32_e32 v129, v218
	v_pk_add_f32 v[124:125], v[128:129], v[124:125]
	v_and_b32_e32 v128, 0xffff0000, v127
	v_mul_f32_e32 v126, 0xbfb8aa3b, v124
	v_exp_f32_e32 v136, v126
	v_and_b32_e32 v127, 0xffff0000, v139
	v_and_b32_e32 v126, 0xffff0000, v135
	v_mov_b32_e32 v206, v215
	v_and_b32_e32 v129, 0xffff0000, v131
	v_and_b32_e32 v131, 0xffff0000, v143
	v_and_b32_e32 v130, 0xffff0000, v147
	v_mov_b32_e32 v202, v155
	v_pk_mul_f32 v[126:127], v[206:207], v[126:127]
	v_mov_b32_e32 v210, v223
	v_pk_fma_f32 v[126:127], v[202:203], v[130:131], v[126:127]
	v_mov_b32_e32 v218, v151
	v_pk_fma_f32 v[126:127], v[210:211], v[128:129], v[126:127]
	v_add_f32_e32 v130, 1.0, v136
	v_pk_add_f32 v[126:127], v[218:219], v[126:127]
	v_rcp_f32_e32 v130, v130
	v_mul_f32_e32 v128, 0xbfb8aa3b, v126
	v_exp_f32_e32 v128, v128
	v_mul_f32_e32 v129, v132, v142
	v_mul_f32_e32 v124, v124, v130
	v_mul_f32_e32 v130, v124, v125
	v_add_f32_e32 v128, 1.0, v128
	v_rcp_f32_e32 v128, v128
	v_mul_f32_e32 v129, v129, v133
	v_mul_f32_e32 v124, v126, v128
	v_mul_f32_e32 v127, v124, v127
	v_cvt_pk_bf16_f32 v124, v156, v170
	v_cvt_pk_bf16_f32 v125, v148, v134
	v_cvt_pk_bf16_f32 v126, v138, v129
	v_cvt_pk_bf16_f32 v127, v130, v127
	s_or_b64 exec, exec, s[66:67]
	v_and_b32_e32 v128, 1, v165
	v_lshlrev_b32_e32 v129, 6, v167
	v_and_or_b32 v128, v129, s57, v128
	v_lshl_or_b32 v131, v166, 8, v128
	v_mov_b64_e32 v[128:129], s[16:17]
	v_ashrrev_i32_e32 v130, 31, v166
	v_mad_u64_u32 v[128:129], s[6:7], v131, s53, v[128:129]
	v_mad_i32_i24 v129, v130, s53, v129
	v_lshl_add_u64 v[128:129], v[158:159], 1, v[128:129]
	global_store_dwordx4 v[128:129], v[124:127], off
	s_mov_b64 exec, s[62:63]
